# differential-attention loop: the cross-half row-max exchange via v_permlane32_swap instead of ds_bpermute (4 sites)
# baseline (speedup 1.0000x reference)
; DI uint4 gld16(const void* p) { uint4 r; asm volatile("global_load_dwordx4 %0, %1, off" : "=v"(r) : "v"(p) : "memory"); return r; }
; DI void vm_wait0() { asm volatile("s_waitcnt vmcnt(0)" ::: "memory"); }
; DI int crow(int i, int h) { return (i & 3) + 8 * (i >> 2) + 4 * h; }
; #define MFMA32(a, b, c) __builtin_amdgcn_mfma_f32_32x32x16_bf16((a), (b), (c), 0, 0, 0)
; DI void kv_wait(KVRegs& rg) { asm volatile("s_waitcnt vmcnt(0)" : "+v"(rg.k[0]), "+v"(rg.k[1]), "+v"(rg.v[0]), "+v"(rg.v[1]) :: "memory"); }
; template <int DQK>
; DI void attn_tile_step(const bf16_t* sK, const bf16_t* sV, const bf16x8 (&qf)[DQK / 16], int k0, int qpos, int window, float sl2, float& m, float& lsum, f32x16 (&O)[2], int r, int h) {
;   constexpr int NKS = DQK / 16, LDK = DQK + 8;
;   f32x16 s[2];
; #pragma unroll
;   for (int t2 = 0; t2 < 2; ++t2) {
; #pragma unroll
;     for (int i = 0; i < 16; ++i) s[t2][i] = 0.f;
; #pragma unroll
;     for (int ks = 0; ks < NKS; ++ks) { const bf16x8 a = *(const bf16x8*)(sK + (t2 * 32 + r) * LDK + ks * 16 + 8 * h); s[t2] = MFMA32(a, qf[ks], s[t2]); }
;   }
;   float mx = m;
; #pragma unroll
;   for (int t2 = 0; t2 < 2; ++t2)
; #pragma unroll
;     for (int i = 0; i < 16; ++i) { const int kpos = k0 + t2 * 32 + crow(i, h); const bool ok = (kpos <= qpos) && (window == 0 || qpos - kpos < window);
;       const float v = ok ? s[t2][i] * sl2 : -1e30f; s[t2][i] = v; mx = fmaxf(mx, v); }
; DI void diff_item(const Params& p, int l, int b, int hh, int qb, char* smem) {
;     ...
;   for (int kt = 0; kt < kt1; ++kt) {
;     const int k0 = kt * 64;
;     kv_wait(rg); vm_wait0();
;     __syncthreads();
;     kv_commit<32>(rg, sK1, sV); *(uint4*)(sK2 + (tid >> 2) * 40 + (tid & 3) * 8) = rk2;
;     __syncthreads();
;     { const int kn = (kt + 1 < kt1 ? kt + 1 : kt) * 64; kv_issue<32>(K1g, vt, kn, rg); rk2 = gld16(K2g + (size_t)(kn + (tid >> 2)) * LDP + (tid & 3) * 8); }
;     if (k0 > qw0 + 31) continue;
.LBB0_537:
	s_waitcnt vmcnt(0)
	v_mov_b32_e32 v66, v170
	s_waitcnt vmcnt(0)
	s_barrier
	s_mov_b32 s2, s37
	v_lshlrev_b32_e32 v67, 4, v66
	v_lshrrev_b32_e32 v65, 2, v66
	v_and_b32_e32 v64, 48, v67
	v_mad_u64_u32 v[64:65], s[0:1], v65, s12, v[64:65]
	v_lshrrev_b32_e32 v65, 3, v66
	ds_write_b128 v64, v[112:115]
	v_and_b32_e32 v64, 0x70, v67
	v_mul_lo_u32 v65, v65, s22
	v_add3_u32 v65, v64, v65, s23
	ds_write2_b64 v65, v[120:121], v[122:123] offset1:1
	v_add_u32_e32 v65, 0x100, v66
	s_add_i32 s37, s37, 1
	v_lshrrev_b32_e32 v65, 3, v65
	s_cmp_ge_u32 s37, s36
	v_mul_lo_u32 v65, v65, s22
	s_cselect_b64 s[8:9], -1, 0
	s_cmp_lt_u32 s37, s36
	v_add3_u32 v64, v64, v65, s23
	s_cselect_b32 s0, s37, s2
	v_mov_b32_e32 v70, v170
	ds_write2_b64 v64, v[124:125], v[126:127] offset1:1
	s_lshl_b32 s2, s0, 6
	ds_write_b128 v208, v[116:119] offset:5120
	s_waitcnt lgkmcnt(0)
	s_barrier
	s_movk_i32 s6, 0x1a00
	v_ashrrev_i32_e32 v66, 2, v70
	v_add_u32_e32 v68, s2, v66
	v_mov_b64_e32 v[66:67], s[34:35]
	v_mad_i64_i32 v[66:67], s[4:5], v68, s6, v[66:67]
	v_lshlrev_b32_e32 v68, 4, v70
	s_lshl_b64 s[0:1], s[2:3], 1
	v_and_b32_e32 v142, 48, v68
	s_add_u32 s0, s30, s0
	v_lshl_add_u64 v[66:67], v[66:67], 0, v[142:143]
	s_addc_u32 s1, s31, s1
	v_lshl_add_u64 v[66:67], v[66:67], 0, s[14:15]
	v_and_b32_e32 v142, 0x70, v68
	global_load_dwordx4 v[112:115], v[66:67], off
	v_lshl_add_u64 v[66:67], s[0:1], 0, v[142:143]
	v_ashrrev_i32_e32 v68, 3, v70
	v_mad_i64_i32 v[68:69], s[0:1], v68, s13, v[66:67]
	global_load_dwordx4 v[120:123], v[68:69], off
	v_add_u32_e32 v68, 0x100, v70
	v_ashrrev_i32_e32 v68, 3, v68
	v_add_u32_e32 v64, s2, v204
	v_mad_i64_i32 v[66:67], s[0:1], v68, s13, v[66:67]
	global_load_dwordx4 v[124:127], v[66:67], off
	v_mad_i64_i32 v[64:65], s[4:5], v64, s6, v[148:149]
	global_load_dwordx4 v[116:119], v[64:65], off
	v_cmp_le_i32_e32 vcc, s21, v205
	s_and_saveexec_b64 s[6:7], vcc
	s_cbranch_execz .LBB0_536
	v_readfirstlane_b32 s0, v205
	s_add_i32 s0, s0, -94
	s_cmp_le_i32 s21, s0
	s_cbranch_scc1 .Ldiff_fast
	ds_read_b128 v[64:67], v206
	ds_read_b128 v[80:83], v206 offset:32
	v_cmp_lt_i32_e32 vcc, v180, v179
	v_add_u32_e32 v142, s21, v203
	v_or_b32_e32 v153, 49, v142
	s_waitcnt vmcnt(3) lgkmcnt(1)
	v_mfma_f32_32x32x16_bf16 v[64:79], v[64:67], v[96:99], 0
	v_cndmask_b32_e32 v84, v177, v180, vcc
	v_lshlrev_b32_e32 v152, 2, v84
	v_or_b32_e32 v158, 48, v142
	s_mov_b32 s2, 0x3e8293ee
	v_cmp_gt_i32_e64 s[0:1], v153, v145
	v_cmp_gt_i32_e64 s[38:39], v158, v140
	v_cmp_gt_i32_e64 s[84:85], v140, v142
	s_waitcnt vmcnt(1) lgkmcnt(0)
	v_mfma_f32_32x32x16_bf16 v[64:79], v[80:83], v[104:107], v[64:79]
	ds_read_b128 v[80:83], v206 offset:2560
	ds_read_b128 v[154:157], v206 offset:2592
	v_cmp_gt_i32_e64 s[86:87], v142, v140
	v_add_u32_e32 v209, 0x2800, v207
	ds_read2_b64 v[136:139], v209 offset1:2
	ds_read2_b64 v[132:135], v209 offset0:4 offset1:6
	v_add_u32_e32 v210, 0x3800, v207
	s_nop 4
	v_mul_f32_e32 v159, 0x3e8293ee, v64
	s_waitcnt lgkmcnt(3)
	v_mfma_f32_32x32x16_bf16 v[80:95], v[80:83], v[96:99], 0
	v_mul_f32_e32 v160, 0x3e8293ee, v65
	v_cndmask_b32_e64 v160, v189, v160, s[84:85]
	v_cndmask_b32_e64 v159, v159, v189, s[86:87]
	s_waitcnt lgkmcnt(2)
	v_mfma_f32_32x32x16_bf16 v[80:95], v[154:157], v[104:107], v[80:95]
	s_nop 11
	v_pk_mul_f32 v[64:65], v[88:89], s[2:3] op_sel_hi:[1,0]
	v_or_b32_e32 v88, 51, v142
	v_or_b32_e32 v89, 50, v142
	v_cndmask_b32_e64 v153, v65, v189, s[0:1]
	v_cndmask_b32_e64 v154, v64, v189, s[38:39]
	v_pk_mul_f32 v[64:65], v[90:91], s[2:3] op_sel_hi:[1,0]
	v_cmp_gt_i32_e64 s[40:41], v88, v145
	v_cmp_gt_i32_e64 s[42:43], v89, v140
	v_or_b32_e32 v88, 57, v142
	v_or_b32_e32 v89, 56, v142
	v_cndmask_b32_e64 v156, v65, v189, s[40:41]
	v_cndmask_b32_e64 v158, v64, v189, s[42:43]
	v_pk_mul_f32 v[64:65], v[92:93], s[2:3] op_sel_hi:[1,0]
	v_cmp_gt_i32_e64 s[44:45], v88, v145
	v_cmp_gt_i32_e64 s[46:47], v89, v140
	v_or_b32_e32 v88, 59, v142
	v_or_b32_e32 v89, 58, v142
	v_cndmask_b32_e64 v90, v65, v189, s[44:45]
	v_cndmask_b32_e64 v91, v64, v189, s[46:47]
	v_pk_mul_f32 v[64:65], v[94:95], s[2:3] op_sel_hi:[1,0]
	v_cmp_gt_i32_e64 s[48:49], v88, v145
	v_cmp_gt_i32_e64 s[50:51], v89, v140
	v_or_b32_e32 v92, 33, v142
	v_or_b32_e32 v93, 32, v142
	v_cndmask_b32_e64 v88, v65, v189, s[48:49]
	v_cndmask_b32_e64 v89, v64, v189, s[50:51]
	v_pk_mul_f32 v[64:65], v[80:81], s[2:3] op_sel_hi:[1,0]
	v_cmp_gt_i32_e64 s[52:53], v92, v145
	v_cmp_gt_i32_e64 s[54:55], v93, v140
	v_or_b32_e32 v92, 35, v142
	v_or_b32_e32 v93, 34, v142
	v_cndmask_b32_e64 v80, v65, v189, s[52:53]
	v_cndmask_b32_e64 v81, v64, v189, s[54:55]
	v_pk_mul_f32 v[64:65], v[82:83], s[2:3] op_sel_hi:[1,0]
	v_cmp_gt_i32_e64 s[56:57], v92, v145
	v_cmp_gt_i32_e64 s[58:59], v93, v140
	v_or_b32_e32 v92, 41, v142
	v_or_b32_e32 v93, 40, v142
	v_cndmask_b32_e64 v82, v65, v189, s[56:57]
	v_cndmask_b32_e64 v83, v64, v189, s[58:59]
	v_pk_mul_f32 v[64:65], v[84:85], s[2:3] op_sel_hi:[1,0]
	v_cmp_gt_i32_e64 s[60:61], v92, v145
	v_cmp_gt_i32_e64 s[62:63], v93, v140
	v_or_b32_e32 v92, 43, v142
	v_or_b32_e32 v93, 42, v142
	v_cndmask_b32_e64 v84, v65, v189, s[60:61]
	v_cndmask_b32_e64 v85, v64, v189, s[62:63]
	v_pk_mul_f32 v[64:65], v[86:87], s[2:3] op_sel_hi:[1,0]
	v_cmp_gt_i32_e64 s[64:65], v92, v145
	v_cmp_gt_i32_e64 s[66:67], v93, v140
	v_or_b32_e32 v92, 17, v142
	v_or_b32_e32 v93, 16, v142
	v_cndmask_b32_e64 v86, v65, v189, s[64:65]
	v_cndmask_b32_e64 v87, v64, v189, s[66:67]
	v_pk_mul_f32 v[64:65], v[72:73], s[2:3] op_sel_hi:[1,0]
	v_cmp_gt_i32_e64 s[68:69], v92, v145
	v_cmp_gt_i32_e64 s[70:71], v93, v140
	v_or_b32_e32 v72, 19, v142
	v_or_b32_e32 v73, 18, v142
	v_cndmask_b32_e64 v92, v65, v189, s[68:69]
; DI float fexp2(float x) { return __builtin_amdgcn_exp2f(x); }
; DI int crow(int i, int h) { return (i & 3) + 8 * (i >> 2) + 4 * h; }
; template <int DQK>
; DI void attn_tile_step(const bf16_t* sK, const bf16_t* sV, const bf16x8 (&qf)[DQK / 16], int k0, int qpos, int window, float sl2, float& m, float& lsum, f32x16 (&O)[2], int r, int h) {
;     ...
;     for (int i = 0; i < 16; ++i) { const int kpos = k0 + t2 * 32 + crow(i, h); const bool ok = (kpos <= qpos) && (window == 0 || qpos - kpos < window);
;       const float v = ok ? s[t2][i] * sl2 : -1e30f; s[t2][i] = v; mx = fmaxf(mx, v); }
;   mx = fmaxf(mx, __shfl_xor(mx, 32));
;   const float corr = fexp2(m - mx); m = mx; float ps = 0.f;
; #pragma unroll
;   for (int t2 = 0; t2 < 2; ++t2)
; #pragma unroll
;     for (int i = 0; i < 16; ++i) { const float pv = (s[t2][i] > -1e29f) ? fexp2(s[t2][i] - mx) : 0.f; s[t2][i] = pv; ps += pv; }
;   lsum = lsum * corr + ps;
; #pragma unroll
;   for (int dt = 0; dt < 2; ++dt)
; #pragma unroll
;     for (int i = 0; i < 16; ++i) O[dt][i] *= corr;
;   pv_accum(s, sV, r, h, O);
	v_cndmask_b32_e64 v93, v64, v189, s[70:71]
	v_pk_mul_f32 v[64:65], v[74:75], s[2:3] op_sel_hi:[1,0]
	v_cmp_gt_i32_e64 s[72:73], v72, v145
	v_cmp_gt_i32_e64 s[74:75], v73, v140
	v_or_b32_e32 v72, 25, v142
	v_or_b32_e32 v73, 24, v142
	v_cndmask_b32_e64 v94, v65, v189, s[72:73]
	v_cndmask_b32_e64 v95, v64, v189, s[74:75]
	v_pk_mul_f32 v[64:65], v[76:77], s[2:3] op_sel_hi:[1,0]
	v_cmp_gt_i32_e64 s[76:77], v72, v145
	v_cmp_gt_i32_e64 s[78:79], v73, v140
	v_or_b32_e32 v72, 27, v142
	v_or_b32_e32 v73, 26, v142
	v_cndmask_b32_e64 v155, v65, v189, s[76:77]
	v_cndmask_b32_e64 v157, v64, v189, s[78:79]
	v_pk_mul_f32 v[64:65], v[78:79], s[2:3] op_sel_hi:[1,0]
	v_cmp_gt_i32_e64 s[80:81], v72, v145
	v_cmp_gt_i32_e64 s[82:83], v73, v140
	v_or_b32_e32 v73, 3, v142
	v_or_b32_e32 v74, 2, v142
	v_cndmask_b32_e64 v161, v65, v189, s[80:81]
	v_cndmask_b32_e64 v162, v64, v189, s[82:83]
	v_pk_mul_f32 v[64:65], v[66:67], s[2:3] op_sel_hi:[1,0]
	v_cmp_gt_i32_e64 s[88:89], v73, v145
	v_cmp_gt_i32_e64 s[90:91], v74, v140
	v_max3_f32 v72, v151, v159, v160
	v_cndmask_b32_e64 v163, v65, v189, s[88:89]
	v_cndmask_b32_e64 v164, v64, v189, s[90:91]
	v_max3_f32 v66, v72, v164, v163
	v_or_b32_e32 v67, 9, v142
	v_or_b32_e32 v72, 8, v142
	v_pk_mul_f32 v[64:65], v[68:69], s[2:3] op_sel_hi:[1,0]
	v_cmp_gt_i32_e64 s[92:93], v67, v145
	v_cmp_gt_i32_e64 s[94:95], v72, v140
	v_or_b32_e32 v67, 11, v142
	v_or_b32_e32 v68, 10, v142
	v_cndmask_b32_e64 v165, v65, v189, s[92:93]
	v_cndmask_b32_e64 v166, v64, v189, s[94:95]
	v_pk_mul_f32 v[64:65], v[70:71], s[2:3] op_sel_hi:[1,0]
	v_cmp_gt_i32_e64 s[96:97], v67, v145
	v_cmp_gt_i32_e32 vcc, v68, v140
	v_max3_f32 v66, v66, v166, v165
	v_cndmask_b32_e64 v142, v65, v189, s[96:97]
	v_cndmask_b32_e32 v167, v64, v189, vcc
	v_max3_f32 v64, v66, v167, v142
	v_max3_f32 v64, v64, v93, v92
	v_max3_f32 v64, v64, v95, v94
	v_max3_f32 v64, v64, v157, v155
	v_max3_f32 v64, v64, v162, v161
	v_max3_f32 v64, v64, v81, v80
	v_max3_f32 v64, v64, v83, v82
	v_max3_f32 v64, v64, v85, v84
	v_max3_f32 v64, v64, v87, v86
	v_max3_f32 v64, v64, v154, v153
	v_max3_f32 v64, v64, v158, v156
	v_max3_f32 v64, v64, v91, v90
	v_max3_f32 v168, v64, v89, v88
	v_mov_b32_e32 v169, v168
	s_nop 1
	v_permlane32_swap_b32_e32 v169, v168
	ds_read2_b64 v[76:79], v210 offset0:32 offset1:34
	ds_read2_b64 v[72:75], v210 offset0:36 offset1:38
	ds_read2_b64 v[68:71], v209 offset0:8 offset1:10
	ds_read2_b64 v[64:67], v210 offset0:40 offset1:42
	s_waitcnt lgkmcnt(4)
	v_max_f32_e32 v169, v169, v169
	v_max_f32_e32 v211, v168, v169
	v_sub_f32_e32 v168, v151, v211
	v_sub_f32_e32 v151, v160, v211
	v_exp_f32_e32 v151, v151
	v_sub_f32_e32 v169, v159, v211
	v_exp_f32_e32 v169, v169
	v_sub_f32_e32 v216, v164, v211
	v_mov_b32_e32 v160, v151
	v_sub_f32_e32 v159, v163, v211
	v_exp_f32_e32 v159, v159
	v_exp_f32_e32 v216, v216
	v_mov_b32_e32 v169, v169
	v_add_f32_e32 v151, 0, v169
	v_add_f32_e32 v151, v160, v151
	v_mov_b32_e32 v163, v159
	v_sub_f32_e32 v159, v165, v211
	v_exp_f32_e32 v159, v159
	v_mov_b32_e32 v164, v216
	v_sub_f32_e32 v216, v166, v211
	v_exp_f32_e32 v216, v216
	v_add_f32_e32 v151, v164, v151
	v_add_f32_e32 v151, v163, v151
	v_mov_b32_e32 v165, v159
	v_sub_f32_e32 v159, v142, v211
	v_exp_f32_e32 v159, v159
	v_mov_b32_e32 v166, v216
	v_sub_f32_e32 v216, v167, v211
	v_exp_f32_e32 v216, v216
	v_add_f32_e32 v151, v166, v151
	v_add_f32_e32 v151, v165, v151
	v_mov_b32_e32 v217, v159
	v_sub_f32_e32 v159, v93, v211
	v_exp_f32_e32 v159, v159
	v_mov_b32_e32 v167, v216
	v_add_f32_e32 v142, v167, v151
	v_sub_f32_e32 v151, v92, v211
	v_exp_f32_e32 v151, v151
	v_add_f32_e32 v142, v217, v142
	s_nop 0
	v_mov_b32_e32 v92, v151
	v_sub_f32_e32 v151, v94, v211
	v_exp_f32_e32 v151, v151
	s_nop 1
	v_mov_b32_e32 v93, v159
	v_sub_f32_e32 v159, v95, v211
	v_exp_f32_e32 v159, v159
	v_add_f32_e32 v142, v93, v142
	v_mov_b32_e32 v94, v151
	v_sub_f32_e32 v151, v155, v211
	v_exp_f32_e32 v151, v151
	v_add_f32_e32 v142, v92, v142
	s_nop 0
	v_mov_b32_e32 v95, v159
	v_sub_f32_e32 v159, v157, v211
	v_exp_f32_e32 v159, v159
	v_sub_f32_e32 v155, v162, v211
	v_mov_b32_e32 v216, v151
	v_sub_f32_e32 v151, v161, v211
	v_exp_f32_e32 v151, v151
	v_exp_f32_e32 v155, v155
	v_add_f32_e32 v142, v95, v142
	v_add_f32_e32 v142, v94, v142
	s_nop 0
	v_mov_b32_e32 v218, v159
	v_add_f32_e32 v142, v218, v142
	v_add_f32_e32 v142, v216, v142
	v_mov_b32_e32 v161, v151
	v_sub_f32_e32 v151, v81, v211
	v_exp_f32_e32 v151, v151
	v_mov_b32_e32 v162, v155
	v_add_f32_e32 v142, v162, v142
	v_add_f32_e32 v219, v161, v142
	v_sub_f32_e32 v142, v80, v211
	v_exp_f32_e32 v142, v142
	v_sub_f32_e32 v80, v82, v211
	v_exp_f32_e32 v80, v80
	v_mov_b32_e32 v220, v142
	v_sub_f32_e32 v81, v83, v211
	v_exp_f32_e32 v81, v81
	v_mov_b32_e32 v221, v151
	v_exp_f32_e32 v142, v168
	v_mov_b32_e32 v222, v80
	v_sub_f32_e32 v80, v84, v211
	v_exp_f32_e32 v80, v80
	v_mov_b32_e32 v223, v81
	v_sub_f32_e32 v81, v85, v211
	v_exp_f32_e32 v81, v81
	v_pk_mul_f32 v[48:49], v[48:49], v[142:143] op_sel_hi:[1,0]
	v_mov_b32_e32 v84, v80
	v_sub_f32_e32 v80, v86, v211
	v_exp_f32_e32 v80, v80
	v_mov_b32_e32 v85, v81
	v_sub_f32_e32 v81, v87, v211
	v_exp_f32_e32 v81, v81
	v_pk_mul_f32 v[50:51], v[50:51], v[142:143] op_sel_hi:[1,0]
	v_pk_mul_f32 v[52:53], v[52:53], v[142:143] op_sel_hi:[1,0]
	v_mov_b32_e32 v159, v80
	v_sub_f32_e32 v80, v153, v211
	v_exp_f32_e32 v80, v80
	v_mov_b32_e32 v86, v81
	v_sub_f32_e32 v81, v154, v211
	v_exp_f32_e32 v81, v81
	v_pk_mul_f32 v[54:55], v[54:55], v[142:143] op_sel_hi:[1,0]
	v_pk_mul_f32 v[56:57], v[56:57], v[142:143] op_sel_hi:[1,0]
	v_mov_b32_e32 v155, v80
	v_sub_f32_e32 v80, v156, v211
	v_exp_f32_e32 v80, v80
	v_mov_b32_e32 v157, v81
	v_sub_f32_e32 v81, v158, v211
	v_exp_f32_e32 v81, v81
	v_mov_b32_e32 v151, v80
	v_sub_f32_e32 v80, v90, v211
	v_exp_f32_e32 v87, v80
	v_mov_b32_e32 v153, v81
	v_pk_mul_f32 v[58:59], v[58:59], v[142:143] op_sel_hi:[1,0]
	v_pk_mul_f32 v[60:61], v[60:61], v[142:143] op_sel_hi:[1,0]
	v_pk_mul_f32 v[62:63], v[62:63], v[142:143] op_sel_hi:[1,0]
	v_cvt_pk_bf16_f32 v83, v167, v217
	v_cvt_pk_bf16_f32 v82, v166, v165
	v_cvt_pk_bf16_f32 v81, v164, v163
	v_cvt_pk_bf16_f32 v80, v169, v160
	v_pk_mul_f32 v[16:17], v[16:17], v[142:143] op_sel_hi:[1,0]
	v_pk_mul_f32 v[18:19], v[18:19], v[142:143] op_sel_hi:[1,0]
	v_mfma_f32_32x32x16_bf16 v[48:63], v[136:139], v[80:83], v[48:63]
	v_mul_f32_e64 v20, v20, v142
	v_mul_f32_e64 v21, v21, v142
	v_mul_f32_e64 v22, v22, v142
	v_mul_f32_e64 v23, v23, v142
	v_mul_f32_e64 v24, v24, v142
	v_mul_f32_e64 v25, v25, v142
	v_pk_mul_f32 v[26:27], v[26:27], v[142:143] op_sel_hi:[1,0]
	v_pk_mul_f32 v[28:29], v[28:29], v[142:143] op_sel_hi:[1,0]
	v_pk_mul_f32 v[30:31], v[30:31], v[142:143] op_sel_hi:[1,0]
	s_waitcnt lgkmcnt(3)
; DI int crow(int i, int h) { return (i & 3) + 8 * (i >> 2) + 4 * h; }
; #define MFMA32(a, b, c) __builtin_amdgcn_mfma_f32_32x32x16_bf16((a), (b), (c), 0, 0, 0)
; DI void pv_accum(const f32x16 (&s)[2], const bf16_t* sV, int r, int h, f32x16 (&O)[2]) {
; #pragma unroll
;   for (int t2 = 0; t2 < 2; ++t2)
; #pragma unroll
;     for (int s2 = 0; s2 < 2; ++s2) {
;       const bf16x8 pf = pack8(s[t2], s2);
; #pragma unroll
;       for (int dt = 0; dt < 2; ++dt) {
;         const bf16_t* vp = sV + (dt * 32 + r) * 68 + t2 * 32 + 16 * s2 + 4 * h;
;         const s16x4 lo = *(const s16x4*)vp, hi = *(const s16x4*)(vp + 8);
;         const bf16x8 vf = __builtin_shufflevector(lo, hi, 0, 1, 2, 3, 4, 5, 6, 7);
;         O[dt] = MFMA32(vf, pf, O[dt]);
;       }
;     }
; }
; template <int DQK>
; DI void attn_tile_step(const bf16_t* sK, const bf16_t* sV, const bf16x8 (&qf)[DQK / 16], int k0, int qpos, int window, float sl2, float& m, float& lsum, f32x16 (&O)[2], int r, int h) {
;   constexpr int NKS = DQK / 16, LDK = DQK + 8;
;   f32x16 s[2];
; #pragma unroll
;   for (int t2 = 0; t2 < 2; ++t2) {
; #pragma unroll
;     for (int i = 0; i < 16; ++i) s[t2][i] = 0.f;
; #pragma unroll
;     for (int ks = 0; ks < NKS; ++ks) { const bf16x8 a = *(const bf16x8*)(sK + (t2 * 32 + r) * LDK + ks * 16 + 8 * h); s[t2] = MFMA32(a, qf[ks], s[t2]); }
;   }
;   float mx = m;
; #pragma unroll
;   for (int t2 = 0; t2 < 2; ++t2)
; #pragma unroll
;     for (int i = 0; i < 16; ++i) { const int kpos = k0 + t2 * 32 + crow(i, h); const bool ok = (kpos <= qpos) && (window == 0 || qpos - kpos < window);
;       const float v = ok ? s[t2][i] * sl2 : -1e30f; s[t2][i] = v; mx = fmaxf(mx, v); }
;   mx = fmaxf(mx, __shfl_xor(mx, 32));
	s_nop 0
	v_mfma_f32_32x32x16_bf16 v[16:31], v[76:79], v[80:83], v[16:31]
	v_cvt_pk_bf16_f32 v79, v162, v161
	v_cvt_pk_bf16_f32 v78, v218, v216
	v_cvt_pk_bf16_f32 v77, v95, v94
	v_cvt_pk_bf16_f32 v76, v93, v92
	v_sub_f32_e32 v80, v91, v211
	v_exp_f32_e32 v80, v80
	v_mfma_f32_32x32x16_bf16 v[48:63], v[132:135], v[76:79], v[48:63]
	v_mov_b32_e32 v161, v87
	s_nop 1
	v_mov_b32_e32 v163, v80
	v_sub_f32_e32 v80, v88, v211
	s_waitcnt lgkmcnt(2)
	v_mfma_f32_32x32x16_bf16 v[16:31], v[72:75], v[76:79], v[16:31]
	v_cvt_pk_bf16_f32 v75, v86, v159
	v_cvt_pk_bf16_f32 v74, v85, v84
	v_cvt_pk_bf16_f32 v73, v223, v222
	v_cvt_pk_bf16_f32 v72, v221, v220
	s_waitcnt lgkmcnt(1)
	s_nop 0
	v_mfma_f32_32x32x16_bf16 v[48:63], v[68:71], v[72:75], v[48:63]
	v_exp_f32_e32 v68, v80
	v_sub_f32_e32 v69, v89, v211
	v_exp_f32_e32 v69, v69
	v_mov_b32_e32 v165, v68
	s_waitcnt lgkmcnt(0)
	v_mfma_f32_32x32x16_bf16 v[16:31], v[64:67], v[72:75], v[16:31]
	v_mov_b32_e32 v167, v69
	ds_read2_b64 v[64:67], v209 offset0:12 offset1:14
	v_cvt_pk_bf16_f32 v71, v167, v165
	v_cvt_pk_bf16_f32 v69, v153, v151
	v_cvt_pk_bf16_f32 v68, v157, v155
	ds_read2_b64 v[72:75], v210 offset0:44 offset1:46
	v_cvt_pk_bf16_f32 v70, v163, v161
	s_waitcnt lgkmcnt(1)
	s_nop 0
	v_mfma_f32_32x32x16_bf16 v[48:63], v[64:67], v[68:71], v[48:63]
	v_add_f32_e32 v64, v221, v219
	v_add_f32_e32 v64, v220, v64
	v_add_f32_e32 v64, v223, v64
	v_add_f32_e32 v64, v222, v64
	v_add_f32_e32 v64, v85, v64
	v_add_f32_e32 v64, v84, v64
	v_add_f32_e32 v169, v86, v64
	s_waitcnt lgkmcnt(0)
	v_mfma_f32_32x32x16_bf16 v[16:31], v[72:75], v[68:71], v[16:31]
	ds_read_b128 v[64:67], v206 offset:5120
	ds_read_b128 v[80:83], v206 offset:5152
	s_waitcnt lgkmcnt(1)
	v_mfma_f32_32x32x16_bf16 v[64:79], v[64:67], v[100:103], 0
	s_waitcnt vmcnt(0) lgkmcnt(0)
	v_mfma_f32_32x32x16_bf16 v[64:79], v[80:83], v[108:111], v[64:79]
	ds_read_b128 v[80:83], v206 offset:7680
	ds_read_b128 v[216:219], v206 offset:7712
	ds_read2_b64 v[136:139], v209 offset1:2
	ds_read2_b64 v[132:135], v209 offset0:4 offset1:6
	s_waitcnt lgkmcnt(3)
	v_mfma_f32_32x32x16_bf16 v[80:95], v[80:83], v[100:103], 0
	s_nop 5
	v_mul_f32_e32 v154, 0x3e8293ee, v64
	v_mul_f32_e32 v156, 0x3e8293ee, v65
	v_cndmask_b32_e64 v156, v189, v156, s[84:85]
	v_cndmask_b32_e64 v154, v154, v189, s[86:87]
	s_waitcnt lgkmcnt(2)
	v_mfma_f32_32x32x16_bf16 v[80:95], v[216:219], v[108:111], v[80:95]
	s_nop 11
	v_pk_mul_f32 v[64:65], v[88:89], s[2:3] op_sel_hi:[1,0]
	s_nop 0
	v_cndmask_b32_e64 v88, v65, v189, s[0:1]
	v_cndmask_b32_e64 v89, v64, v189, s[38:39]
	v_pk_mul_f32 v[64:65], v[90:91], s[2:3] op_sel_hi:[1,0]
	s_nop 0
	v_cndmask_b32_e64 v90, v65, v189, s[40:41]
	v_cndmask_b32_e64 v91, v64, v189, s[42:43]
	v_pk_mul_f32 v[64:65], v[92:93], s[2:3] op_sel_hi:[1,0]
	s_nop 0
	v_cndmask_b32_e64 v92, v65, v189, s[44:45]
	v_cndmask_b32_e64 v93, v64, v189, s[46:47]
	v_pk_mul_f32 v[64:65], v[94:95], s[2:3] op_sel_hi:[1,0]
	s_nop 0
	v_cndmask_b32_e64 v94, v65, v189, s[48:49]
	v_cndmask_b32_e64 v95, v64, v189, s[50:51]
	v_pk_mul_f32 v[64:65], v[80:81], s[2:3] op_sel_hi:[1,0]
	s_nop 0
	v_cndmask_b32_e64 v80, v65, v189, s[52:53]
	v_cndmask_b32_e64 v81, v64, v189, s[54:55]
	v_pk_mul_f32 v[64:65], v[82:83], s[2:3] op_sel_hi:[1,0]
	s_nop 0
	v_cndmask_b32_e64 v82, v65, v189, s[56:57]
	v_cndmask_b32_e64 v83, v64, v189, s[58:59]
	v_pk_mul_f32 v[64:65], v[84:85], s[2:3] op_sel_hi:[1,0]
	s_nop 0
	v_cndmask_b32_e64 v84, v65, v189, s[60:61]
	v_cndmask_b32_e64 v85, v64, v189, s[62:63]
	v_pk_mul_f32 v[64:65], v[86:87], s[2:3] op_sel_hi:[1,0]
	s_nop 0
	v_cndmask_b32_e64 v86, v65, v189, s[64:65]
	v_cndmask_b32_e64 v87, v64, v189, s[66:67]
	v_pk_mul_f32 v[64:65], v[72:73], s[2:3] op_sel_hi:[1,0]
	v_max3_f32 v72, v150, v154, v156
	v_cndmask_b32_e64 v158, v65, v189, s[68:69]
	v_cndmask_b32_e64 v160, v64, v189, s[70:71]
	v_pk_mul_f32 v[64:65], v[74:75], s[2:3] op_sel_hi:[1,0]
	s_nop 0
	v_cndmask_b32_e64 v162, v65, v189, s[72:73]
	v_cndmask_b32_e64 v164, v64, v189, s[74:75]
	v_pk_mul_f32 v[64:65], v[76:77], s[2:3] op_sel_hi:[1,0]
	s_nop 0
	v_cndmask_b32_e64 v166, v65, v189, s[76:77]
	v_cndmask_b32_e64 v168, v64, v189, s[78:79]
	v_pk_mul_f32 v[64:65], v[78:79], s[2:3] op_sel_hi:[1,0]
	s_nop 0
	v_cndmask_b32_e64 v216, v65, v189, s[80:81]
	v_cndmask_b32_e64 v217, v64, v189, s[82:83]
	v_pk_mul_f32 v[64:65], v[66:67], s[2:3] op_sel_hi:[1,0]
	s_nop 0
	v_cndmask_b32_e64 v218, v65, v189, s[88:89]
	v_cndmask_b32_e64 v219, v64, v189, s[90:91]
	v_pk_mul_f32 v[64:65], v[68:69], s[2:3] op_sel_hi:[1,0]
	v_max3_f32 v66, v72, v219, v218
	v_cndmask_b32_e64 v220, v65, v189, s[92:93]
	v_cndmask_b32_e64 v221, v64, v189, s[94:95]
	v_pk_mul_f32 v[64:65], v[70:71], s[2:3] op_sel_hi:[1,0]
	v_max3_f32 v66, v66, v221, v220
	v_cndmask_b32_e64 v222, v65, v189, s[96:97]
	v_cndmask_b32_e32 v223, v64, v189, vcc
	v_max3_f32 v64, v66, v223, v222
	v_max3_f32 v64, v64, v160, v158
	v_max3_f32 v64, v64, v164, v162
	v_max3_f32 v64, v64, v168, v166
	v_max3_f32 v64, v64, v217, v216
	v_max3_f32 v64, v64, v81, v80
	v_max3_f32 v64, v64, v83, v82
	v_max3_f32 v64, v64, v85, v84
	v_max3_f32 v64, v64, v87, v86
	v_max3_f32 v64, v64, v89, v88
	v_max3_f32 v64, v64, v91, v90
	v_max3_f32 v64, v64, v93, v92
	v_max3_f32 v224, v64, v95, v94
	v_mov_b32_e32 v152, v224
	s_nop 1
	v_permlane32_swap_b32_e32 v152, v224
	ds_read2_b64 v[76:79], v210 offset0:32 offset1:34
	ds_read2_b64 v[72:75], v210 offset0:36 offset1:38
	ds_read2_b64 v[68:71], v209 offset0:8 offset1:10
	ds_read2_b64 v[64:67], v210 offset0:40 offset1:42
	s_waitcnt lgkmcnt(4)
; DI float fexp2(float x) { return __builtin_amdgcn_exp2f(x); }
; DI int crow(int i, int h) { return (i & 3) + 8 * (i >> 2) + 4 * h; }
; #define MFMA32(a, b, c) __builtin_amdgcn_mfma_f32_32x32x16_bf16((a), (b), (c), 0, 0, 0)
; DI void pv_accum(const f32x16 (&s)[2], const bf16_t* sV, int r, int h, f32x16 (&O)[2]) {
; #pragma unroll
;   for (int t2 = 0; t2 < 2; ++t2)
; #pragma unroll
;     for (int s2 = 0; s2 < 2; ++s2) {
;       const bf16x8 pf = pack8(s[t2], s2);
; #pragma unroll
;       for (int dt = 0; dt < 2; ++dt) {
;         const bf16_t* vp = sV + (dt * 32 + r) * 68 + t2 * 32 + 16 * s2 + 4 * h;
;         const s16x4 lo = *(const s16x4*)vp, hi = *(const s16x4*)(vp + 8);
;         const bf16x8 vf = __builtin_shufflevector(lo, hi, 0, 1, 2, 3, 4, 5, 6, 7);
;         O[dt] = MFMA32(vf, pf, O[dt]);
;       }
;     }
; }
; template <int DQK>
; DI void attn_tile_step(const bf16_t* sK, const bf16_t* sV, const bf16x8 (&qf)[DQK / 16], int k0, int qpos, int window, float sl2, float& m, float& lsum, f32x16 (&O)[2], int r, int h) {
;   constexpr int NKS = DQK / 16, LDK = DQK + 8;
;   f32x16 s[2];
; #pragma unroll
;   for (int t2 = 0; t2 < 2; ++t2) {
; #pragma unroll
;     for (int i = 0; i < 16; ++i) s[t2][i] = 0.f;
; #pragma unroll
;     for (int ks = 0; ks < NKS; ++ks) { const bf16x8 a = *(const bf16x8*)(sK + (t2 * 32 + r) * LDK + ks * 16 + 8 * h); s[t2] = MFMA32(a, qf[ks], s[t2]); }
;   }
;   float mx = m;
; #pragma unroll
;   for (int t2 = 0; t2 < 2; ++t2)
; #pragma unroll
;     for (int i = 0; i < 16; ++i) { const int kpos = k0 + t2 * 32 + crow(i, h); const bool ok = (kpos <= qpos) && (window == 0 || qpos - kpos < window);
;       const float v = ok ? s[t2][i] * sl2 : -1e30f; s[t2][i] = v; mx = fmaxf(mx, v); }
;   mx = fmaxf(mx, __shfl_xor(mx, 32));
;   const float corr = fexp2(m - mx); m = mx; float ps = 0.f;
; #pragma unroll
;   for (int t2 = 0; t2 < 2; ++t2)
; #pragma unroll
;     for (int i = 0; i < 16; ++i) { const float pv = (s[t2][i] > -1e29f) ? fexp2(s[t2][i] - mx) : 0.f; s[t2][i] = pv; ps += pv; }
;   lsum = lsum * corr + ps;
; #pragma unroll
;   for (int dt = 0; dt < 2; ++dt)
; #pragma unroll
;     for (int i = 0; i < 16; ++i) O[dt][i] *= corr;
;   pv_accum(s, sV, r, h, O);
	v_max_f32_e32 v152, v152, v152
	v_max_f32_e32 v224, v224, v152
	v_sub_f32_e32 v225, v150, v224
	v_sub_f32_e32 v150, v156, v224
	v_exp_f32_e32 v150, v150
	v_sub_f32_e32 v152, v154, v224
	v_exp_f32_e32 v152, v152
	v_mov_b32_e32 v226, v150
	v_sub_f32_e32 v154, v219, v224
	v_exp_f32_e32 v154, v154
	v_mov_b32_e32 v227, v152
	v_sub_f32_e32 v152, v218, v224
	v_exp_f32_e32 v152, v152
	v_add_f32_e32 v150, 0, v227
	v_add_f32_e32 v150, v226, v150
	v_mov_b32_e32 v218, v152
	v_sub_f32_e32 v152, v220, v224
	v_exp_f32_e32 v152, v152
	s_nop 1
	v_mov_b32_e32 v219, v154
	v_sub_f32_e32 v154, v221, v224
	v_exp_f32_e32 v154, v154
	v_add_f32_e32 v150, v219, v150
	v_add_f32_e32 v150, v218, v150
	v_mov_b32_e32 v220, v152
	v_sub_f32_e32 v152, v222, v224
	v_exp_f32_e32 v152, v152
	s_nop 1
	v_mov_b32_e32 v221, v154
	v_sub_f32_e32 v154, v223, v224
	v_exp_f32_e32 v154, v154
	v_add_f32_e32 v150, v221, v150
	v_add_f32_e32 v150, v220, v150
	v_mov_b32_e32 v222, v152
	v_sub_f32_e32 v152, v158, v224
	v_exp_f32_e32 v152, v152
	s_nop 1
	v_mov_b32_e32 v223, v154
	v_sub_f32_e32 v154, v160, v224
	v_exp_f32_e32 v154, v154
	v_add_f32_e32 v150, v223, v150
	v_add_f32_e32 v150, v222, v150
	v_mov_b32_e32 v228, v152
	v_sub_f32_e32 v152, v162, v224
	v_exp_f32_e32 v152, v152
	s_nop 1
	v_mov_b32_e32 v160, v154
	v_sub_f32_e32 v154, v164, v224
	v_exp_f32_e32 v154, v154
	v_add_f32_e32 v150, v160, v150
	v_add_f32_e32 v150, v228, v150
	v_mov_b32_e32 v162, v152
	v_sub_f32_e32 v152, v166, v224
	v_exp_f32_e32 v152, v152
	s_nop 1
	v_mov_b32_e32 v164, v154
	v_sub_f32_e32 v154, v168, v224
	v_exp_f32_e32 v154, v154
	v_add_f32_e32 v150, v164, v150
	v_add_f32_e32 v150, v162, v150
	v_mov_b32_e32 v166, v152
	v_sub_f32_e32 v152, v216, v224
	v_exp_f32_e32 v152, v152
	s_nop 1
	v_mov_b32_e32 v229, v154
	v_sub_f32_e32 v154, v217, v224
	v_exp_f32_e32 v154, v154
	v_add_f32_e32 v150, v229, v150
	v_add_f32_e32 v150, v166, v150
	v_mov_b32_e32 v216, v152
	v_sub_f32_e32 v152, v80, v224
	v_exp_f32_e32 v152, v152
	s_nop 1
	v_mov_b32_e32 v217, v154
	v_sub_f32_e32 v154, v81, v224
	v_exp_f32_e32 v154, v154
	v_add_f32_e32 v150, v217, v150
	v_add_f32_e32 v150, v216, v150
	v_mov_b32_e32 v230, v152
	v_sub_f32_e32 v81, v82, v224
	v_exp_f32_e32 v81, v81
	v_mov_b32_e32 v231, v154
	v_add_f32_e32 v80, v231, v150
	v_sub_f32_e32 v150, v83, v224
	v_exp_f32_e32 v150, v150
	v_sub_f32_e32 v82, v85, v224
	v_mov_b32_e32 v232, v81
	v_sub_f32_e32 v81, v84, v224
	v_exp_f32_e32 v81, v81
	v_exp_f32_e32 v82, v82
	v_add_f32_e32 v80, v230, v80
	v_mov_b32_e32 v233, v150
	v_add_f32_e32 v80, v233, v80
	v_add_f32_e32 v80, v232, v80
	v_mov_b32_e32 v234, v81
	v_sub_f32_e32 v81, v86, v224
	v_exp_f32_e32 v81, v81
	v_mov_b32_e32 v235, v82
	v_sub_f32_e32 v82, v87, v224
	v_exp_f32_e32 v82, v82
	v_add_f32_e32 v80, v235, v80
	v_add_f32_e32 v80, v234, v80
	v_mov_b32_e32 v158, v81
	v_sub_f32_e32 v81, v89, v224
	v_exp_f32_e32 v81, v81
	v_mov_b32_e32 v86, v82
	v_add_f32_e32 v168, v86, v80
	v_sub_f32_e32 v80, v88, v224
	v_exp_f32_e32 v80, v80
	s_nop 0
	v_mov_b32_e32 v154, v80
	v_sub_f32_e32 v80, v90, v224
	v_exp_f32_e32 v80, v80
	v_mov_b32_e32 v156, v81
	v_sub_f32_e32 v81, v91, v224
	v_exp_f32_e32 v81, v81
	v_mov_b32_e32 v150, v80
	v_sub_f32_e32 v80, v93, v224
	v_exp_f32_e32 v87, v80
	v_exp_f32_e32 v80, v225
	v_mov_b32_e32 v152, v81
	v_sub_f32_e32 v81, v92, v224
	v_exp_f32_e32 v88, v81
	v_mov_b32_e32 v81, v142
	v_pk_mul_f32 v[46:47], v[46:47], v[80:81] op_sel_hi:[1,0]
	v_pk_mul_f32 v[44:45], v[44:45], v[80:81] op_sel_hi:[1,0]
	v_pk_mul_f32 v[42:43], v[42:43], v[80:81] op_sel_hi:[1,0]
	v_pk_mul_f32 v[40:41], v[40:41], v[80:81] op_sel_hi:[1,0]
	v_pk_mul_f32 v[38:39], v[38:39], v[80:81] op_sel_hi:[1,0]
	v_pk_mul_f32 v[36:37], v[36:37], v[80:81] op_sel_hi:[1,0]
	v_pk_mul_f32 v[34:35], v[34:35], v[80:81] op_sel_hi:[1,0]
	v_pk_mul_f32 v[32:33], v[32:33], v[80:81] op_sel_hi:[1,0]
	v_cvt_pk_bf16_f32 v85, v223, v222
	v_cvt_pk_bf16_f32 v84, v221, v220
	v_cvt_pk_bf16_f32 v83, v219, v218
	v_cvt_pk_bf16_f32 v82, v227, v226
	v_pk_mul_f32 v[14:15], v[14:15], v[80:81] op_sel_hi:[1,0]
	v_pk_mul_f32 v[12:13], v[12:13], v[80:81] op_sel_hi:[1,0]
	v_mfma_f32_32x32x16_bf16 v[32:47], v[136:139], v[82:85], v[32:47]
	v_mul_f32_e64 v10, v10, v80
	v_mul_f32_e64 v11, v11, v80
	v_mul_f32_e64 v8, v8, v80
	v_mul_f32_e64 v9, v9, v80
	v_mul_f32_e64 v6, v6, v80
	v_mul_f32_e64 v7, v7, v80
	v_pk_mul_f32 v[4:5], v[4:5], v[80:81] op_sel_hi:[1,0]
	v_pk_mul_f32 v[2:3], v[2:3], v[80:81] op_sel_hi:[1,0]
	v_pk_mul_f32 v[0:1], v[0:1], v[80:81] op_sel_hi:[1,0]
	s_waitcnt lgkmcnt(3)
	s_nop 0
	v_mfma_f32_32x32x16_bf16 v[0:15], v[76:79], v[82:85], v[0:15]
	v_cvt_pk_bf16_f32 v79, v217, v216
	v_cvt_pk_bf16_f32 v78, v229, v166
	v_cvt_pk_bf16_f32 v77, v164, v162
	v_cvt_pk_bf16_f32 v76, v160, v228
	v_sub_f32_e32 v83, v94, v224
	v_sub_f32_e32 v82, v95, v224
	v_mfma_f32_32x32x16_bf16 v[32:47], v[132:135], v[76:79], v[32:47]
	v_exp_f32_e32 v83, v83
	v_exp_f32_e32 v82, v82
	v_mov_b32_e32 v160, v88
	s_nop 1
	v_mov_b32_e32 v162, v87
	s_waitcnt lgkmcnt(2)
	v_mfma_f32_32x32x16_bf16 v[0:15], v[72:75], v[76:79], v[0:15]
	v_cvt_pk_bf16_f32 v75, v86, v158
	v_cvt_pk_bf16_f32 v74, v235, v234
	v_cvt_pk_bf16_f32 v73, v233, v232
	v_cvt_pk_bf16_f32 v72, v231, v230
	s_waitcnt lgkmcnt(1)
	s_nop 0
	v_mfma_f32_32x32x16_bf16 v[32:47], v[68:71], v[72:75], v[32:47]
	v_mov_b32_e32 v164, v83
	v_add_f32_e64 v68, v158, v168
	v_add_f32_e64 v69, v159, v169
	v_mov_b32_e32 v166, v82
	v_pk_add_f32 v[68:69], v[156:157], v[68:69]
	v_pk_add_f32 v[76:77], v[154:155], v[68:69]
	s_waitcnt lgkmcnt(0)
	v_mfma_f32_32x32x16_bf16 v[0:15], v[64:67], v[72:75], v[0:15]
	ds_read2_b64 v[64:67], v209 offset0:12 offset1:14
	v_cvt_pk_bf16_f32 v71, v166, v164
	v_cvt_pk_bf16_f32 v69, v152, v150
	v_cvt_pk_bf16_f32 v68, v156, v154
	ds_read2_b64 v[72:75], v210 offset0:44 offset1:46
	v_cvt_pk_bf16_f32 v70, v162, v160
	s_waitcnt lgkmcnt(1)
	s_nop 0
	v_mfma_f32_32x32x16_bf16 v[32:47], v[64:67], v[68:71], v[32:47]
	v_add_f32_e64 v64, v152, v76
	v_add_f32_e64 v65, v153, v77
	v_add_f32_e64 v64, v150, v64
	v_add_f32_e64 v65, v151, v65
	v_add_f32_e64 v64, v162, v64
	v_add_f32_e64 v65, v163, v65
	v_pk_add_f32 v[64:65], v[160:161], v[64:65]
	s_waitcnt lgkmcnt(0)
	v_mfma_f32_32x32x16_bf16 v[0:15], v[72:75], v[68:71], v[0:15]
	v_add_f32_e64 v64, v166, v64
	v_add_f32_e64 v65, v167, v65
	v_add_f32_e64 v64, v164, v64
	v_add_f32_e64 v65, v165, v65
	v_fma_f32 v146, v146, v80, v64
	v_fma_f32 v147, v147, v81, v65
	v_mov_b32_e32 v151, v211
	v_mov_b32_e32 v150, v224
	s_branch .LBB0_536
; DI float fexp2(float x) { return __builtin_amdgcn_exp2f(x); }
; DI int crow(int i, int h) { return (i & 3) + 8 * (i >> 2) + 4 * h; }
; #define MFMA32(a, b, c) __builtin_amdgcn_mfma_f32_32x32x16_bf16((a), (b), (c), 0, 0, 0)
; template <int DQK>
; DI void attn_tile_step(const bf16_t* sK, const bf16_t* sV, const bf16x8 (&qf)[DQK / 16], int k0, int qpos, int window, float sl2, float& m, float& lsum, f32x16 (&O)[2], int r, int h) {
;   constexpr int NKS = DQK / 16, LDK = DQK + 8;
;   f32x16 s[2];
; #pragma unroll
;   for (int t2 = 0; t2 < 2; ++t2) {
; #pragma unroll
;     for (int i = 0; i < 16; ++i) s[t2][i] = 0.f;
; #pragma unroll
;     for (int ks = 0; ks < NKS; ++ks) { const bf16x8 a = *(const bf16x8*)(sK + (t2 * 32 + r) * LDK + ks * 16 + 8 * h); s[t2] = MFMA32(a, qf[ks], s[t2]); }
;   }
;   float mx = m;
; #pragma unroll
;   for (int t2 = 0; t2 < 2; ++t2)
; #pragma unroll
;     for (int i = 0; i < 16; ++i) { const int kpos = k0 + t2 * 32 + crow(i, h); const bool ok = (kpos <= qpos) && (window == 0 || qpos - kpos < window);
;       const float v = ok ? s[t2][i] * sl2 : -1e30f; s[t2][i] = v; mx = fmaxf(mx, v); }
;   mx = fmaxf(mx, __shfl_xor(mx, 32));
;   const float corr = fexp2(m - mx); m = mx; float ps = 0.f;
; #pragma unroll
;   for (int t2 = 0; t2 < 2; ++t2)
; #pragma unroll
;     for (int i = 0; i < 16; ++i) { const float pv = (s[t2][i] > -1e29f) ? fexp2(s[t2][i] - mx) : 0.f; s[t2][i] = pv; ps += pv; }
.Ldiff_fast:
	ds_read_b128 v[64:67], v206
	ds_read_b128 v[80:83], v206 offset:32
	v_cmp_lt_i32_e32 vcc, v180, v179
	v_add_u32_e32 v142, s21, v203
	s_waitcnt vmcnt(3) lgkmcnt(1)
	v_mfma_f32_32x32x16_bf16 v[64:79], v[64:67], v[96:99], 0
	v_cndmask_b32_e32 v84, v177, v180, vcc
	v_lshlrev_b32_e32 v152, 2, v84
	s_mov_b32 s2, 0x3e8293ee
	s_waitcnt vmcnt(1) lgkmcnt(0)
	v_mfma_f32_32x32x16_bf16 v[64:79], v[80:83], v[104:107], v[64:79]
	ds_read_b128 v[80:83], v206 offset:2560
	ds_read_b128 v[154:157], v206 offset:2592
	v_add_u32_e32 v209, 0x2800, v207
	ds_read2_b64 v[136:139], v209 offset1:2
	ds_read2_b64 v[132:135], v209 offset0:4 offset1:6
	v_add_u32_e32 v210, 0x3800, v207
	s_nop 4
	s_nop 0
	v_mul_f32_e32 v159, 0x3e8293ee, v64
	s_waitcnt lgkmcnt(3)
	v_mfma_f32_32x32x16_bf16 v[80:95], v[80:83], v[96:99], 0
	v_mul_f32_e32 v160, 0x3e8293ee, v65
	s_waitcnt lgkmcnt(2)
	v_mfma_f32_32x32x16_bf16 v[80:95], v[154:157], v[104:107], v[80:95]
	s_nop 11
	v_mul_f32_e32 v154, s2, v88
	v_mul_f32_e32 v153, s2, v89
	v_mul_f32_e32 v158, s2, v90
	v_mul_f32_e32 v156, s2, v91
	v_mul_f32_e32 v91, s2, v92
	v_mul_f32_e32 v90, s2, v93
	v_mul_f32_e32 v89, s2, v94
	v_mul_f32_e32 v88, s2, v95
	v_pk_mul_f32 v[64:65], v[80:81], s[2:3] op_sel_hi:[1,0]
	v_mov_b32_e32 v80, v65
	v_mov_b32_e32 v81, v64
	v_pk_mul_f32 v[64:65], v[82:83], s[2:3] op_sel_hi:[1,0]
	v_mov_b32_e32 v82, v65
	v_mov_b32_e32 v83, v64
	v_pk_mul_f32 v[64:65], v[84:85], s[2:3] op_sel_hi:[1,0]
	v_mov_b32_e32 v84, v65
	v_mov_b32_e32 v85, v64
	v_pk_mul_f32 v[64:65], v[86:87], s[2:3] op_sel_hi:[1,0]
	v_mov_b32_e32 v86, v65
	v_mov_b32_e32 v87, v64
	v_mul_f32_e32 v93, s2, v72
	v_mul_f32_e32 v92, s2, v73
	v_mul_f32_e32 v95, s2, v74
	v_mul_f32_e32 v94, s2, v75
	v_mul_f32_e32 v157, s2, v76
	v_mul_f32_e32 v155, s2, v77
	v_mul_f32_e32 v162, s2, v78
	v_mul_f32_e32 v161, s2, v79
	v_mul_f32_e32 v164, s2, v66
	v_mul_f32_e32 v163, s2, v67
	v_max3_f32 v72, v151, v159, v160
	v_max3_f32 v66, v72, v164, v163
	v_mul_f32_e32 v166, s2, v68
	v_mul_f32_e32 v165, s2, v69
	v_mul_f32_e32 v167, s2, v70
	v_mul_f32_e32 v142, s2, v71
	v_max3_f32 v66, v66, v166, v165
	v_max3_f32 v64, v66, v167, v142
	v_max3_f32 v64, v64, v93, v92
	v_max3_f32 v64, v64, v95, v94
	v_max3_f32 v64, v64, v157, v155
	v_max3_f32 v64, v64, v162, v161
	v_max3_f32 v64, v64, v81, v80
	v_max3_f32 v64, v64, v83, v82
	v_max3_f32 v64, v64, v85, v84
	v_max3_f32 v64, v64, v87, v86
	v_max3_f32 v64, v64, v154, v153
	v_max3_f32 v64, v64, v158, v156
	v_max3_f32 v64, v64, v91, v90
	v_max3_f32 v168, v64, v89, v88
	v_mov_b32_e32 v169, v168
	s_nop 1
	v_permlane32_swap_b32_e32 v169, v168
	ds_read2_b64 v[76:79], v210 offset0:32 offset1:34
	ds_read2_b64 v[72:75], v210 offset0:36 offset1:38
	ds_read2_b64 v[68:71], v209 offset0:8 offset1:10
	ds_read2_b64 v[64:67], v210 offset0:40 offset1:42
	s_waitcnt lgkmcnt(4)
	v_max_f32_e32 v169, v169, v169
	v_max_f32_e32 v211, v168, v169
	v_sub_f32_e32 v168, v151, v211
	v_sub_f32_e32 v151, v160, v211
	v_exp_f32_e32 v160, v151
	v_sub_f32_e32 v169, v159, v211
	v_exp_f32_e32 v169, v169
	v_sub_f32_e32 v216, v164, v211
	v_sub_f32_e32 v159, v163, v211
	v_exp_f32_e32 v163, v159
	v_exp_f32_e32 v164, v216
	v_add_f32_e32 v151, 0, v169
	v_add_f32_e32 v151, v160, v151
	v_sub_f32_e32 v159, v165, v211
	v_exp_f32_e32 v165, v159
	v_sub_f32_e32 v216, v166, v211
	v_exp_f32_e32 v166, v216
	v_add_f32_e32 v151, v164, v151
	v_add_f32_e32 v151, v163, v151
	v_sub_f32_e32 v159, v142, v211
	v_exp_f32_e32 v217, v159
	v_sub_f32_e32 v216, v167, v211
	v_exp_f32_e32 v167, v216
	v_add_f32_e32 v151, v166, v151
	v_add_f32_e32 v151, v165, v151
	v_sub_f32_e32 v159, v93, v211
	v_exp_f32_e32 v93, v159
	v_add_f32_e32 v142, v167, v151
	v_sub_f32_e32 v151, v92, v211
	v_exp_f32_e32 v92, v151
	v_add_f32_e32 v142, v217, v142
	s_nop 0
	v_sub_f32_e32 v151, v94, v211
	v_exp_f32_e32 v94, v151
	s_nop 1
	v_sub_f32_e32 v159, v95, v211
	v_exp_f32_e32 v95, v159
	v_add_f32_e32 v142, v93, v142
	v_sub_f32_e32 v151, v155, v211
	v_exp_f32_e32 v216, v151
	v_add_f32_e32 v142, v92, v142
	s_nop 0
	v_sub_f32_e32 v159, v157, v211
	v_exp_f32_e32 v218, v159
	v_sub_f32_e32 v155, v162, v211
	v_sub_f32_e32 v151, v161, v211
	v_exp_f32_e32 v161, v151
	v_exp_f32_e32 v162, v155
	v_add_f32_e32 v142, v95, v142
	v_add_f32_e32 v142, v94, v142
	s_nop 0
	v_add_f32_e32 v142, v218, v142
	v_add_f32_e32 v142, v216, v142
	v_sub_f32_e32 v151, v81, v211
	v_exp_f32_e32 v221, v151
	v_add_f32_e32 v142, v162, v142
	v_add_f32_e32 v219, v161, v142
	v_sub_f32_e32 v142, v80, v211
	v_exp_f32_e32 v220, v142
	v_sub_f32_e32 v80, v82, v211
	v_exp_f32_e32 v222, v80
	v_sub_f32_e32 v81, v83, v211
	v_exp_f32_e32 v223, v81
	v_exp_f32_e32 v142, v168
	v_sub_f32_e32 v80, v84, v211
	v_exp_f32_e32 v84, v80
	v_sub_f32_e32 v81, v85, v211
	v_exp_f32_e32 v85, v81
	v_pk_mul_f32 v[48:49], v[48:49], v[142:143] op_sel_hi:[1,0]
	v_sub_f32_e32 v80, v86, v211
	v_exp_f32_e32 v159, v80
	v_sub_f32_e32 v81, v87, v211
	v_exp_f32_e32 v86, v81
	v_pk_mul_f32 v[50:51], v[50:51], v[142:143] op_sel_hi:[1,0]
	v_pk_mul_f32 v[52:53], v[52:53], v[142:143] op_sel_hi:[1,0]
	v_sub_f32_e32 v80, v153, v211
	v_exp_f32_e32 v155, v80
	v_sub_f32_e32 v81, v154, v211
	v_exp_f32_e32 v157, v81
	v_pk_mul_f32 v[54:55], v[54:55], v[142:143] op_sel_hi:[1,0]
	v_pk_mul_f32 v[56:57], v[56:57], v[142:143] op_sel_hi:[1,0]
	v_sub_f32_e32 v80, v156, v211
	v_exp_f32_e32 v151, v80
	v_sub_f32_e32 v81, v158, v211
	v_exp_f32_e32 v153, v81
	v_sub_f32_e32 v80, v90, v211
	v_exp_f32_e32 v87, v80
	v_pk_mul_f32 v[58:59], v[58:59], v[142:143] op_sel_hi:[1,0]
	v_pk_mul_f32 v[60:61], v[60:61], v[142:143] op_sel_hi:[1,0]
	v_pk_mul_f32 v[62:63], v[62:63], v[142:143] op_sel_hi:[1,0]
	v_cvt_pk_bf16_f32 v83, v167, v217
	v_cvt_pk_bf16_f32 v82, v166, v165
	v_cvt_pk_bf16_f32 v81, v164, v163
	v_cvt_pk_bf16_f32 v80, v169, v160
	v_pk_mul_f32 v[16:17], v[16:17], v[142:143] op_sel_hi:[1,0]
	v_pk_mul_f32 v[18:19], v[18:19], v[142:143] op_sel_hi:[1,0]
	v_mfma_f32_32x32x16_bf16 v[48:63], v[136:139], v[80:83], v[48:63]
	v_mul_f32_e64 v20, v20, v142
	v_mul_f32_e64 v21, v21, v142
	v_mul_f32_e64 v22, v22, v142
	v_mul_f32_e64 v23, v23, v142
	v_mul_f32_e64 v24, v24, v142
	v_mul_f32_e64 v25, v25, v142
	v_pk_mul_f32 v[26:27], v[26:27], v[142:143] op_sel_hi:[1,0]
	v_pk_mul_f32 v[28:29], v[28:29], v[142:143] op_sel_hi:[1,0]
	v_pk_mul_f32 v[30:31], v[30:31], v[142:143] op_sel_hi:[1,0]
	s_waitcnt lgkmcnt(3)
; DI int crow(int i, int h) { return (i & 3) + 8 * (i >> 2) + 4 * h; }
; #define MFMA32(a, b, c) __builtin_amdgcn_mfma_f32_32x32x16_bf16((a), (b), (c), 0, 0, 0)
; DI void pv_accum(const f32x16 (&s)[2], const bf16_t* sV, int r, int h, f32x16 (&O)[2]) {
; #pragma unroll
;   for (int t2 = 0; t2 < 2; ++t2)
; #pragma unroll
;     for (int s2 = 0; s2 < 2; ++s2) {
;       const bf16x8 pf = pack8(s[t2], s2);
; #pragma unroll
;       for (int dt = 0; dt < 2; ++dt) {
;         const bf16_t* vp = sV + (dt * 32 + r) * 68 + t2 * 32 + 16 * s2 + 4 * h;
;         const s16x4 lo = *(const s16x4*)vp, hi = *(const s16x4*)(vp + 8);
;         const bf16x8 vf = __builtin_shufflevector(lo, hi, 0, 1, 2, 3, 4, 5, 6, 7);
;         O[dt] = MFMA32(vf, pf, O[dt]);
;       }
;     }
; }
; template <int DQK>
; DI void attn_tile_step(const bf16_t* sK, const bf16_t* sV, const bf16x8 (&qf)[DQK / 16], int k0, int qpos, int window, float sl2, float& m, float& lsum, f32x16 (&O)[2], int r, int h) {
;   constexpr int NKS = DQK / 16, LDK = DQK + 8;
;   f32x16 s[2];
; #pragma unroll
;   for (int t2 = 0; t2 < 2; ++t2) {
; #pragma unroll
;     for (int i = 0; i < 16; ++i) s[t2][i] = 0.f;
; #pragma unroll
;     for (int ks = 0; ks < NKS; ++ks) { const bf16x8 a = *(const bf16x8*)(sK + (t2 * 32 + r) * LDK + ks * 16 + 8 * h); s[t2] = MFMA32(a, qf[ks], s[t2]); }
;   }
;   float mx = m;
; #pragma unroll
;   for (int t2 = 0; t2 < 2; ++t2)
; #pragma unroll
;     for (int i = 0; i < 16; ++i) { const int kpos = k0 + t2 * 32 + crow(i, h); const bool ok = (kpos <= qpos) && (window == 0 || qpos - kpos < window);
;       const float v = ok ? s[t2][i] * sl2 : -1e30f; s[t2][i] = v; mx = fmaxf(mx, v); }
;   mx = fmaxf(mx, __shfl_xor(mx, 32));
	s_nop 0
	v_mfma_f32_32x32x16_bf16 v[16:31], v[76:79], v[80:83], v[16:31]
	v_cvt_pk_bf16_f32 v79, v162, v161
	v_cvt_pk_bf16_f32 v78, v218, v216
	v_cvt_pk_bf16_f32 v77, v95, v94
	v_cvt_pk_bf16_f32 v76, v93, v92
	v_sub_f32_e32 v80, v91, v211
	v_exp_f32_e32 v163, v80
	v_mfma_f32_32x32x16_bf16 v[48:63], v[132:135], v[76:79], v[48:63]
	v_mov_b32_e32 v161, v87
	s_nop 1
	v_sub_f32_e32 v80, v88, v211
	s_waitcnt lgkmcnt(2)
	v_mfma_f32_32x32x16_bf16 v[16:31], v[72:75], v[76:79], v[16:31]
	v_cvt_pk_bf16_f32 v75, v86, v159
	v_cvt_pk_bf16_f32 v74, v85, v84
	v_cvt_pk_bf16_f32 v73, v223, v222
	v_cvt_pk_bf16_f32 v72, v221, v220
	s_waitcnt lgkmcnt(1)
	s_nop 0
	v_mfma_f32_32x32x16_bf16 v[48:63], v[68:71], v[72:75], v[48:63]
	v_exp_f32_e32 v165, v80
	v_sub_f32_e32 v69, v89, v211
	v_exp_f32_e32 v167, v69
	s_waitcnt lgkmcnt(0)
	v_mfma_f32_32x32x16_bf16 v[16:31], v[64:67], v[72:75], v[16:31]
	ds_read2_b64 v[64:67], v209 offset0:12 offset1:14
	v_cvt_pk_bf16_f32 v71, v167, v165
	v_cvt_pk_bf16_f32 v69, v153, v151
	v_cvt_pk_bf16_f32 v68, v157, v155
	ds_read2_b64 v[72:75], v210 offset0:44 offset1:46
	v_cvt_pk_bf16_f32 v70, v163, v161
	s_waitcnt lgkmcnt(1)
	s_nop 0
	v_mfma_f32_32x32x16_bf16 v[48:63], v[64:67], v[68:71], v[48:63]
	v_add_f32_e32 v64, v221, v219
	v_add_f32_e32 v64, v220, v64
	v_add_f32_e32 v64, v223, v64
	v_add_f32_e32 v64, v222, v64
	v_add_f32_e32 v64, v85, v64
	v_add_f32_e32 v64, v84, v64
	v_add_f32_e32 v169, v86, v64
	s_waitcnt lgkmcnt(0)
	v_mfma_f32_32x32x16_bf16 v[16:31], v[72:75], v[68:71], v[16:31]
	ds_read_b128 v[64:67], v206 offset:5120
	ds_read_b128 v[80:83], v206 offset:5152
	s_waitcnt lgkmcnt(1)
	v_mfma_f32_32x32x16_bf16 v[64:79], v[64:67], v[100:103], 0
	s_waitcnt vmcnt(0) lgkmcnt(0)
	v_mfma_f32_32x32x16_bf16 v[64:79], v[80:83], v[108:111], v[64:79]
	ds_read_b128 v[80:83], v206 offset:7680
	ds_read_b128 v[216:219], v206 offset:7712
	ds_read2_b64 v[136:139], v209 offset1:2
	ds_read2_b64 v[132:135], v209 offset0:4 offset1:6
	s_waitcnt lgkmcnt(3)
	v_mfma_f32_32x32x16_bf16 v[80:95], v[80:83], v[100:103], 0
	s_nop 5
	v_mul_f32_e32 v154, 0x3e8293ee, v64
	v_mul_f32_e32 v156, 0x3e8293ee, v65
	s_waitcnt lgkmcnt(2)
	v_mfma_f32_32x32x16_bf16 v[80:95], v[216:219], v[108:111], v[80:95]
	s_nop 11
	v_pk_mul_f32 v[64:65], v[88:89], s[2:3] op_sel_hi:[1,0]
	s_nop 0
	v_mov_b32_e32 v88, v65
	v_mov_b32_e32 v89, v64
	v_pk_mul_f32 v[64:65], v[90:91], s[2:3] op_sel_hi:[1,0]
	s_nop 0
	v_mov_b32_e32 v90, v65
	v_mov_b32_e32 v91, v64
	v_pk_mul_f32 v[64:65], v[92:93], s[2:3] op_sel_hi:[1,0]
	s_nop 0
	v_mov_b32_e32 v92, v65
	v_mov_b32_e32 v93, v64
	v_pk_mul_f32 v[64:65], v[94:95], s[2:3] op_sel_hi:[1,0]
	s_nop 0
	v_mov_b32_e32 v94, v65
	v_mov_b32_e32 v95, v64
	v_pk_mul_f32 v[64:65], v[80:81], s[2:3] op_sel_hi:[1,0]
	s_nop 0
	v_mov_b32_e32 v80, v65
	v_mov_b32_e32 v81, v64
	v_pk_mul_f32 v[64:65], v[82:83], s[2:3] op_sel_hi:[1,0]
	s_nop 0
	v_mov_b32_e32 v82, v65
	v_mov_b32_e32 v83, v64
	v_pk_mul_f32 v[64:65], v[84:85], s[2:3] op_sel_hi:[1,0]
	s_nop 0
	v_mov_b32_e32 v84, v65
	v_mov_b32_e32 v85, v64
	v_pk_mul_f32 v[64:65], v[86:87], s[2:3] op_sel_hi:[1,0]
	s_nop 0
	v_mov_b32_e32 v86, v65
	v_mov_b32_e32 v87, v64
	v_mul_f32_e32 v160, s2, v72
	v_mul_f32_e32 v158, s2, v73
	v_max3_f32 v72, v150, v154, v156
	v_mul_f32_e32 v164, s2, v74
	v_mul_f32_e32 v162, s2, v75
	s_nop 0
	v_mul_f32_e32 v168, s2, v76
	v_mul_f32_e32 v166, s2, v77
	s_nop 0
	v_mul_f32_e32 v217, s2, v78
	v_mul_f32_e32 v216, s2, v79
	s_nop 0
	v_mul_f32_e32 v219, s2, v66
	v_mul_f32_e32 v218, s2, v67
	s_nop 0
	v_mul_f32_e32 v221, s2, v68
	v_mul_f32_e32 v220, s2, v69
	v_max3_f32 v66, v72, v219, v218
	v_mul_f32_e32 v223, s2, v70
	v_mul_f32_e32 v222, s2, v71
	v_max3_f32 v66, v66, v221, v220
	v_max3_f32 v64, v66, v223, v222
	v_max3_f32 v64, v64, v160, v158
	v_max3_f32 v64, v64, v164, v162
	v_max3_f32 v64, v64, v168, v166
	v_max3_f32 v64, v64, v217, v216
	v_max3_f32 v64, v64, v81, v80
	v_max3_f32 v64, v64, v83, v82
	v_max3_f32 v64, v64, v85, v84
	v_max3_f32 v64, v64, v87, v86
	v_max3_f32 v64, v64, v89, v88
	v_max3_f32 v64, v64, v91, v90
	v_max3_f32 v64, v64, v93, v92
	v_max3_f32 v224, v64, v95, v94
	v_mov_b32_e32 v152, v224
	s_nop 1
	v_permlane32_swap_b32_e32 v152, v224
	ds_read2_b64 v[76:79], v210 offset0:32 offset1:34
	ds_read2_b64 v[72:75], v210 offset0:36 offset1:38
	ds_read2_b64 v[68:71], v209 offset0:8 offset1:10
	ds_read2_b64 v[64:67], v210 offset0:40 offset1:42
	s_waitcnt lgkmcnt(4)
; DI float fexp2(float x) { return __builtin_amdgcn_exp2f(x); }
; DI int crow(int i, int h) { return (i & 3) + 8 * (i >> 2) + 4 * h; }
; #define MFMA32(a, b, c) __builtin_amdgcn_mfma_f32_32x32x16_bf16((a), (b), (c), 0, 0, 0)
; DI void pv_accum(const f32x16 (&s)[2], const bf16_t* sV, int r, int h, f32x16 (&O)[2]) {
; #pragma unroll
;   for (int t2 = 0; t2 < 2; ++t2)
; #pragma unroll
;     for (int s2 = 0; s2 < 2; ++s2) {
;       const bf16x8 pf = pack8(s[t2], s2);
; #pragma unroll
;       for (int dt = 0; dt < 2; ++dt) {
;         const bf16_t* vp = sV + (dt * 32 + r) * 68 + t2 * 32 + 16 * s2 + 4 * h;
;         const s16x4 lo = *(const s16x4*)vp, hi = *(const s16x4*)(vp + 8);
;         const bf16x8 vf = __builtin_shufflevector(lo, hi, 0, 1, 2, 3, 4, 5, 6, 7);
;         O[dt] = MFMA32(vf, pf, O[dt]);
;       }
;     }
; }
; template <int DQK>
; DI void attn_tile_step(const bf16_t* sK, const bf16_t* sV, const bf16x8 (&qf)[DQK / 16], int k0, int qpos, int window, float sl2, float& m, float& lsum, f32x16 (&O)[2], int r, int h) {
;   constexpr int NKS = DQK / 16, LDK = DQK + 8;
;   f32x16 s[2];
; #pragma unroll
;   for (int t2 = 0; t2 < 2; ++t2) {
; #pragma unroll
;     for (int i = 0; i < 16; ++i) s[t2][i] = 0.f;
; #pragma unroll
;     for (int ks = 0; ks < NKS; ++ks) { const bf16x8 a = *(const bf16x8*)(sK + (t2 * 32 + r) * LDK + ks * 16 + 8 * h); s[t2] = MFMA32(a, qf[ks], s[t2]); }
;   }
;   float mx = m;
; #pragma unroll
;   for (int t2 = 0; t2 < 2; ++t2)
; #pragma unroll
;     for (int i = 0; i < 16; ++i) { const int kpos = k0 + t2 * 32 + crow(i, h); const bool ok = (kpos <= qpos) && (window == 0 || qpos - kpos < window);
;       const float v = ok ? s[t2][i] * sl2 : -1e30f; s[t2][i] = v; mx = fmaxf(mx, v); }
;   mx = fmaxf(mx, __shfl_xor(mx, 32));
;   const float corr = fexp2(m - mx); m = mx; float ps = 0.f;
; #pragma unroll
;   for (int t2 = 0; t2 < 2; ++t2)
; #pragma unroll
;     for (int i = 0; i < 16; ++i) { const float pv = (s[t2][i] > -1e29f) ? fexp2(s[t2][i] - mx) : 0.f; s[t2][i] = pv; ps += pv; }
;   lsum = lsum * corr + ps;
; #pragma unroll
;   for (int dt = 0; dt < 2; ++dt)
; #pragma unroll
;     for (int i = 0; i < 16; ++i) O[dt][i] *= corr;
;   pv_accum(s, sV, r, h, O);
	v_max_f32_e32 v152, v152, v152
	v_max_f32_e32 v224, v224, v152
	v_sub_f32_e32 v225, v150, v224
	v_sub_f32_e32 v150, v156, v224
	v_exp_f32_e32 v226, v150
	v_sub_f32_e32 v152, v154, v224
	v_exp_f32_e32 v227, v152
	v_sub_f32_e32 v154, v219, v224
	v_exp_f32_e32 v219, v154
	v_sub_f32_e32 v152, v218, v224
	v_exp_f32_e32 v218, v152
	v_add_f32_e32 v150, 0, v227
	v_add_f32_e32 v150, v226, v150
	v_sub_f32_e32 v152, v220, v224
	v_exp_f32_e32 v220, v152
	s_nop 1
	v_sub_f32_e32 v154, v221, v224
	v_exp_f32_e32 v221, v154
	v_add_f32_e32 v150, v219, v150
	v_add_f32_e32 v150, v218, v150
	v_sub_f32_e32 v152, v222, v224
	v_exp_f32_e32 v222, v152
	s_nop 1
	v_sub_f32_e32 v154, v223, v224
	v_exp_f32_e32 v223, v154
	v_add_f32_e32 v150, v221, v150
	v_add_f32_e32 v150, v220, v150
	v_sub_f32_e32 v152, v158, v224
	v_exp_f32_e32 v228, v152
	s_nop 1
	v_sub_f32_e32 v154, v160, v224
	v_exp_f32_e32 v160, v154
	v_add_f32_e32 v150, v223, v150
	v_add_f32_e32 v150, v222, v150
	v_sub_f32_e32 v152, v162, v224
	v_exp_f32_e32 v162, v152
	s_nop 1
	v_sub_f32_e32 v154, v164, v224
	v_exp_f32_e32 v164, v154
	v_add_f32_e32 v150, v160, v150
	v_add_f32_e32 v150, v228, v150
	v_sub_f32_e32 v152, v166, v224
	v_exp_f32_e32 v166, v152
	s_nop 1
	v_sub_f32_e32 v154, v168, v224
	v_exp_f32_e32 v229, v154
	v_add_f32_e32 v150, v164, v150
	v_add_f32_e32 v150, v162, v150
	v_sub_f32_e32 v152, v216, v224
	v_exp_f32_e32 v216, v152
	s_nop 1
	v_sub_f32_e32 v154, v217, v224
	v_exp_f32_e32 v217, v154
	v_add_f32_e32 v150, v229, v150
	v_add_f32_e32 v150, v166, v150
	v_sub_f32_e32 v152, v80, v224
	v_exp_f32_e32 v230, v152
	s_nop 1
	v_sub_f32_e32 v154, v81, v224
	v_exp_f32_e32 v231, v154
	v_add_f32_e32 v150, v217, v150
	v_add_f32_e32 v150, v216, v150
	v_sub_f32_e32 v81, v82, v224
	v_exp_f32_e32 v232, v81
	v_add_f32_e32 v80, v231, v150
	v_sub_f32_e32 v150, v83, v224
	v_exp_f32_e32 v233, v150
	v_sub_f32_e32 v82, v85, v224
	v_sub_f32_e32 v81, v84, v224
	v_exp_f32_e32 v234, v81
	v_exp_f32_e32 v235, v82
	v_add_f32_e32 v80, v230, v80
	v_add_f32_e32 v80, v233, v80
	v_add_f32_e32 v80, v232, v80
	v_sub_f32_e32 v81, v86, v224
	v_exp_f32_e32 v158, v81
	v_sub_f32_e32 v82, v87, v224
	v_exp_f32_e32 v86, v82
	v_add_f32_e32 v80, v235, v80
	v_add_f32_e32 v80, v234, v80
	v_sub_f32_e32 v81, v89, v224
	v_exp_f32_e32 v156, v81
	v_add_f32_e32 v168, v86, v80
	v_sub_f32_e32 v80, v88, v224
	v_exp_f32_e32 v154, v80
	s_nop 0
	v_sub_f32_e32 v80, v90, v224
	v_exp_f32_e32 v150, v80
	v_sub_f32_e32 v81, v91, v224
	v_exp_f32_e32 v152, v81
	v_sub_f32_e32 v80, v93, v224
	v_exp_f32_e32 v87, v80
	v_exp_f32_e32 v80, v225
	v_sub_f32_e32 v81, v92, v224
	v_exp_f32_e32 v88, v81
	v_mov_b32_e32 v81, v142
	v_pk_mul_f32 v[46:47], v[46:47], v[80:81] op_sel_hi:[1,0]
	v_pk_mul_f32 v[44:45], v[44:45], v[80:81] op_sel_hi:[1,0]
	v_pk_mul_f32 v[42:43], v[42:43], v[80:81] op_sel_hi:[1,0]
	v_pk_mul_f32 v[40:41], v[40:41], v[80:81] op_sel_hi:[1,0]
	v_pk_mul_f32 v[38:39], v[38:39], v[80:81] op_sel_hi:[1,0]
	v_pk_mul_f32 v[36:37], v[36:37], v[80:81] op_sel_hi:[1,0]
	v_pk_mul_f32 v[34:35], v[34:35], v[80:81] op_sel_hi:[1,0]
	v_pk_mul_f32 v[32:33], v[32:33], v[80:81] op_sel_hi:[1,0]
	v_cvt_pk_bf16_f32 v85, v223, v222
	v_cvt_pk_bf16_f32 v84, v221, v220
	v_cvt_pk_bf16_f32 v83, v219, v218
	v_cvt_pk_bf16_f32 v82, v227, v226
	v_pk_mul_f32 v[14:15], v[14:15], v[80:81] op_sel_hi:[1,0]
	v_pk_mul_f32 v[12:13], v[12:13], v[80:81] op_sel_hi:[1,0]
	v_mfma_f32_32x32x16_bf16 v[32:47], v[136:139], v[82:85], v[32:47]
	v_mul_f32_e64 v10, v10, v80
	v_mul_f32_e64 v11, v11, v80
	v_mul_f32_e64 v8, v8, v80
	v_mul_f32_e64 v9, v9, v80
	v_mul_f32_e64 v6, v6, v80
	v_mul_f32_e64 v7, v7, v80
	v_pk_mul_f32 v[4:5], v[4:5], v[80:81] op_sel_hi:[1,0]
	v_pk_mul_f32 v[2:3], v[2:3], v[80:81] op_sel_hi:[1,0]
	v_pk_mul_f32 v[0:1], v[0:1], v[80:81] op_sel_hi:[1,0]
	s_waitcnt lgkmcnt(3)
	s_nop 0
	v_mfma_f32_32x32x16_bf16 v[0:15], v[76:79], v[82:85], v[0:15]
	v_cvt_pk_bf16_f32 v79, v217, v216
	v_cvt_pk_bf16_f32 v78, v229, v166
	v_cvt_pk_bf16_f32 v77, v164, v162
	v_cvt_pk_bf16_f32 v76, v160, v228
	v_sub_f32_e32 v83, v94, v224
	v_sub_f32_e32 v82, v95, v224
	v_mfma_f32_32x32x16_bf16 v[32:47], v[132:135], v[76:79], v[32:47]
	v_exp_f32_e32 v164, v83
	v_exp_f32_e32 v166, v82
	v_mov_b32_e32 v160, v88
	s_nop 1
	v_mov_b32_e32 v162, v87
	s_waitcnt lgkmcnt(2)
	v_mfma_f32_32x32x16_bf16 v[0:15], v[72:75], v[76:79], v[0:15]
	v_cvt_pk_bf16_f32 v75, v86, v158
	v_cvt_pk_bf16_f32 v74, v235, v234
	v_cvt_pk_bf16_f32 v73, v233, v232
	v_cvt_pk_bf16_f32 v72, v231, v230
	s_waitcnt lgkmcnt(1)
	s_nop 0
	v_mfma_f32_32x32x16_bf16 v[32:47], v[68:71], v[72:75], v[32:47]
	v_add_f32_e64 v68, v158, v168
	v_add_f32_e64 v69, v159, v169
	v_pk_add_f32 v[68:69], v[156:157], v[68:69]
	v_pk_add_f32 v[76:77], v[154:155], v[68:69]
	s_waitcnt lgkmcnt(0)
	v_mfma_f32_32x32x16_bf16 v[0:15], v[64:67], v[72:75], v[0:15]
	ds_read2_b64 v[64:67], v209 offset0:12 offset1:14
	v_cvt_pk_bf16_f32 v71, v166, v164
	v_cvt_pk_bf16_f32 v69, v152, v150
	v_cvt_pk_bf16_f32 v68, v156, v154
	ds_read2_b64 v[72:75], v210 offset0:44 offset1:46
	v_cvt_pk_bf16_f32 v70, v162, v160
	s_waitcnt lgkmcnt(1)
	s_nop 0
	v_mfma_f32_32x32x16_bf16 v[32:47], v[64:67], v[68:71], v[32:47]
	v_add_f32_e64 v64, v152, v76
	v_add_f32_e64 v65, v153, v77
	v_add_f32_e64 v64, v150, v64
	v_add_f32_e64 v65, v151, v65
	v_add_f32_e64 v64, v162, v64
	v_add_f32_e64 v65, v163, v65
	v_pk_add_f32 v[64:65], v[160:161], v[64:65]
	s_waitcnt lgkmcnt(0)
	v_mfma_f32_32x32x16_bf16 v[0:15], v[72:75], v[68:71], v[0:15]
	v_add_f32_e64 v64, v166, v64
	v_add_f32_e64 v65, v167, v65
	v_add_f32_e64 v64, v164, v64
	v_add_f32_e64 v65, v165, v65
	v_fma_f32 v146, v146, v80, v64
	v_fma_f32 v147, v147, v81, v65
	v_mov_b32_e32 v151, v211
	v_mov_b32_e32 v150, v224
	s_branch .LBB0_536
